# SwiGLU GEMM mainloops: STAGE(As00) LDS-DMA pair moved from load segment 2 to load segment 3 (6/2 -> 4/4), counted waits re-derived
# speedup vs baseline: 1.0056x; 1.0027x over previous
.LBB0_103:
	s_add_u32 s0, s24, 0xfff80080
	s_addc_u32 s1, s25, -1
	s_add_i32 s59, 0, 0x10000
	s_cmp_eq_u32 s61, 28
	s_cselect_b32 s31, s17, s1
	s_cselect_b32 s30, s51, s0
	s_cselect_b32 s29, s15, s52
	s_cselect_b32 s28, s34, s35
	s_add_i32 s63, 0, 0x14000
	v_add_u32_e32 v154, s59, v147
	v_add_u32_e32 v170, s63, v147
	ds_read_b128 v[138:141], v154
	ds_read_b128 v[142:145], v154 offset:1024
	ds_read_b128 v[150:153], v154 offset:2048
	ds_read_b128 v[154:157], v154 offset:3072
	ds_read_b128 v[158:161], v170
	ds_read_b128 v[162:165], v170 offset:1024
	ds_read_b128 v[166:169], v170 offset:2048
	ds_read_b128 v[170:173], v170 offset:3072
	v_lshl_add_u64 v[220:221], s[24:25], 0, v[134:135]
	s_add_i32 m0, s40, 0xc000
	ds_read_b128 v[174:177], v149
	ds_read_b128 v[178:181], v149 offset:1024
	ds_read_b128 v[182:185], v149 offset:2048
	ds_read_b128 v[186:189], v149 offset:3072
	ds_read_b128 v[190:193], v149 offset:4096
	ds_read_b128 v[194:197], v149 offset:5120
	ds_read_b128 v[212:215], v149 offset:6144
	ds_read_b128 v[216:219], v149 offset:7168
	global_load_lds_dwordx4 v[220:221], off
	v_lshl_add_u64 v[220:221], s[24:25], 0, v[136:137]
	s_add_i32 m0, s40, 0xe000
	s_nop 0
	global_load_lds_dwordx4 v[220:221], off
	s_waitcnt vmcnt(8)
	s_waitcnt lgkmcnt(0)
	s_barrier
	s_setprio 1
	s_waitcnt lgkmcnt(0)
	v_mfma_f32_16x16x32_bf16 v[124:127], v[138:141], v[174:177], v[124:127]
	v_mfma_f32_16x16x32_bf16 v[116:119], v[150:153], v[174:177], v[116:119]
	v_mfma_f32_16x16x32_bf16 v[108:111], v[138:141], v[182:185], v[108:111]
	v_mfma_f32_16x16x32_bf16 v[96:99], v[150:153], v[182:185], v[96:99]
	v_mfma_f32_16x16x32_bf16 v[88:91], v[138:141], v[190:193], v[88:91]
	v_mfma_f32_16x16x32_bf16 v[80:83], v[150:153], v[190:193], v[80:83]
	v_mfma_f32_16x16x32_bf16 v[72:75], v[138:141], v[212:215], v[72:75]
	v_mfma_f32_16x16x32_bf16 v[64:67], v[150:153], v[212:215], v[64:67]
	v_mfma_f32_16x16x32_bf16 v[124:127], v[142:145], v[178:181], v[124:127]
	v_mfma_f32_16x16x32_bf16 v[116:119], v[154:157], v[178:181], v[116:119]
	v_mfma_f32_16x16x32_bf16 v[108:111], v[142:145], v[186:189], v[108:111]
	v_mfma_f32_16x16x32_bf16 v[96:99], v[154:157], v[186:189], v[96:99]
	v_mfma_f32_16x16x32_bf16 v[88:91], v[142:145], v[194:197], v[88:91]
	v_mfma_f32_16x16x32_bf16 v[80:83], v[154:157], v[194:197], v[80:83]
	v_mfma_f32_16x16x32_bf16 v[72:75], v[142:145], v[216:219], v[72:75]
	v_mfma_f32_16x16x32_bf16 v[64:67], v[154:157], v[216:219], v[64:67]
	s_setprio 0
	s_setprio 1
	v_mfma_f32_16x16x32_bf16 v[120:123], v[158:161], v[174:177], v[120:123]
	v_mfma_f32_16x16x32_bf16 v[112:115], v[166:169], v[174:177], v[112:115]
	v_mfma_f32_16x16x32_bf16 v[104:107], v[158:161], v[182:185], v[104:107]
	v_mfma_f32_16x16x32_bf16 v[100:103], v[166:169], v[182:185], v[100:103]
	v_mfma_f32_16x16x32_bf16 v[92:95], v[158:161], v[190:193], v[92:95]
	v_mfma_f32_16x16x32_bf16 v[84:87], v[166:169], v[190:193], v[84:87]
	v_mfma_f32_16x16x32_bf16 v[76:79], v[158:161], v[212:215], v[76:79]
	v_mfma_f32_16x16x32_bf16 v[68:71], v[166:169], v[212:215], v[68:71]
	v_mfma_f32_16x16x32_bf16 v[120:123], v[162:165], v[178:181], v[120:123]
	v_mfma_f32_16x16x32_bf16 v[112:115], v[170:173], v[178:181], v[112:115]
	v_mfma_f32_16x16x32_bf16 v[104:107], v[162:165], v[186:189], v[104:107]
	v_mfma_f32_16x16x32_bf16 v[100:103], v[170:173], v[186:189], v[100:103]
	v_mfma_f32_16x16x32_bf16 v[92:95], v[162:165], v[194:197], v[92:95]
	v_mfma_f32_16x16x32_bf16 v[84:87], v[170:173], v[194:197], v[84:87]
	v_mfma_f32_16x16x32_bf16 v[76:79], v[162:165], v[216:219], v[76:79]
	v_mfma_f32_16x16x32_bf16 v[68:71], v[170:173], v[216:219], v[68:71]
	s_setprio 0
	s_barrier
	s_add_i32 s0, s59, s38
	v_lshl_add_u64 v[220:221], s[28:29], 0, v[198:199]
	s_mov_b32 m0, s0
	ds_read_b128 v[174:177], v149 offset:16384
	ds_read_b128 v[178:181], v149 offset:17408
	ds_read_b128 v[182:185], v149 offset:18432
	ds_read_b128 v[186:189], v149 offset:19456
	ds_read_b128 v[190:193], v149 offset:20480
	ds_read_b128 v[194:197], v149 offset:21504
	ds_read_b128 v[212:215], v149 offset:22528
	ds_read_b128 v[216:219], v149 offset:23552
	global_load_lds_dwordx4 v[220:221], off
	s_add_i32 m0, s0, 0x2000
	s_add_u32 s0, s28, 0x80000
	v_lshl_add_u64 v[222:223], s[28:29], 0, v[128:129]
	s_addc_u32 s1, s29, 0
	s_add_i32 s59, s63, s38
	global_load_lds_dwordx4 v[222:223], off
	v_lshl_add_u64 v[224:225], s[0:1], 0, v[198:199]
	s_mov_b32 m0, s59
	v_lshl_add_u64 v[226:227], s[30:31], 0, v[130:131]
	global_load_lds_dwordx4 v[224:225], off
	v_lshl_add_u64 v[224:225], s[0:1], 0, v[128:129]
	s_add_i32 m0, s59, 0x2000
	s_nop 0
	global_load_lds_dwordx4 v[224:225], off
	s_waitcnt vmcnt(6)
	s_waitcnt lgkmcnt(0)
	s_barrier
	s_setprio 1
	s_waitcnt lgkmcnt(0)
	v_mfma_f32_16x16x32_bf16 v[56:59], v[138:141], v[174:177], v[56:59]
	v_mfma_f32_16x16x32_bf16 v[48:51], v[150:153], v[174:177], v[48:51]
	v_mfma_f32_16x16x32_bf16 v[40:43], v[138:141], v[182:185], v[40:43]
	v_mfma_f32_16x16x32_bf16 v[32:35], v[150:153], v[182:185], v[32:35]
	v_mfma_f32_16x16x32_bf16 v[24:27], v[138:141], v[190:193], v[24:27]
	v_mfma_f32_16x16x32_bf16 v[16:19], v[150:153], v[190:193], v[16:19]
	v_mfma_f32_16x16x32_bf16 v[8:11], v[138:141], v[212:215], v[8:11]
	v_mfma_f32_16x16x32_bf16 v[0:3], v[150:153], v[212:215], v[0:3]
	v_mfma_f32_16x16x32_bf16 v[56:59], v[142:145], v[178:181], v[56:59]
	v_mfma_f32_16x16x32_bf16 v[48:51], v[154:157], v[178:181], v[48:51]
	v_mfma_f32_16x16x32_bf16 v[40:43], v[142:145], v[186:189], v[40:43]
	v_mfma_f32_16x16x32_bf16 v[32:35], v[154:157], v[186:189], v[32:35]
	v_mfma_f32_16x16x32_bf16 v[24:27], v[142:145], v[194:197], v[24:27]
	v_mfma_f32_16x16x32_bf16 v[16:19], v[154:157], v[194:197], v[16:19]
	v_mfma_f32_16x16x32_bf16 v[8:11], v[142:145], v[216:219], v[8:11]
	v_mfma_f32_16x16x32_bf16 v[0:3], v[154:157], v[216:219], v[0:3]
	s_setprio 0
	s_setprio 1
	v_mfma_f32_16x16x32_bf16 v[60:63], v[158:161], v[174:177], v[60:63]
	v_mfma_f32_16x16x32_bf16 v[52:55], v[166:169], v[174:177], v[52:55]
	v_mfma_f32_16x16x32_bf16 v[44:47], v[158:161], v[182:185], v[44:47]
	v_mfma_f32_16x16x32_bf16 v[36:39], v[166:169], v[182:185], v[36:39]
	v_mfma_f32_16x16x32_bf16 v[28:31], v[158:161], v[190:193], v[28:31]
	v_mfma_f32_16x16x32_bf16 v[20:23], v[166:169], v[190:193], v[20:23]
	v_mfma_f32_16x16x32_bf16 v[12:15], v[158:161], v[212:215], v[12:15]
	v_mfma_f32_16x16x32_bf16 v[4:7], v[166:169], v[212:215], v[4:7]
	v_mfma_f32_16x16x32_bf16 v[60:63], v[162:165], v[178:181], v[60:63]
	v_mfma_f32_16x16x32_bf16 v[52:55], v[170:173], v[178:181], v[52:55]
	v_mfma_f32_16x16x32_bf16 v[44:47], v[162:165], v[186:189], v[44:47]
	v_mfma_f32_16x16x32_bf16 v[36:39], v[170:173], v[186:189], v[36:39]
	v_mfma_f32_16x16x32_bf16 v[28:31], v[162:165], v[194:197], v[28:31]
	v_mfma_f32_16x16x32_bf16 v[20:23], v[170:173], v[194:197], v[20:23]
	v_mfma_f32_16x16x32_bf16 v[12:15], v[162:165], v[216:219], v[12:15]
	v_mfma_f32_16x16x32_bf16 v[4:7], v[170:173], v[216:219], v[4:7]
	s_setprio 0
	s_barrier
	s_add_i32 s59, 0, 0x18000
	s_add_i32 s63, 0, 0x1c000
	v_add_u32_e32 v154, s59, v147
	v_add_u32_e32 v170, s63, v147
	ds_read_b128 v[138:141], v154
	ds_read_b128 v[142:145], v154 offset:1024
	ds_read_b128 v[150:153], v154 offset:2048
	ds_read_b128 v[154:157], v154 offset:3072
	ds_read_b128 v[158:161], v170
	ds_read_b128 v[162:165], v170 offset:1024
	ds_read_b128 v[166:169], v170 offset:2048
	ds_read_b128 v[170:173], v170 offset:3072
	s_add_u32 s0, s30, 0x80000
	s_addc_u32 s1, s31, 0
	s_mov_b32 m0, s42
	v_lshl_add_u64 v[228:229], s[0:1], 0, v[132:133]
	ds_read_b128 v[174:177], v149 offset:32768
	ds_read_b128 v[178:181], v149 offset:33792
	ds_read_b128 v[182:185], v149 offset:34816
	ds_read_b128 v[186:189], v149 offset:35840
	ds_read_b128 v[190:193], v149 offset:36864
	ds_read_b128 v[194:197], v149 offset:37888
	ds_read_b128 v[212:215], v149 offset:38912
	ds_read_b128 v[216:219], v149 offset:39936
	global_load_lds_dwordx4 v[228:229], off
	v_lshl_add_u64 v[228:229], s[0:1], 0, v[130:131]
	s_mov_b32 m0, s43
	s_nop 0
	global_load_lds_dwordx4 v[228:229], off
	v_lshl_add_u64 v[224:225], s[30:31], 0, v[132:133]
	s_mov_b32 m0, s40
	s_nop 0
	global_load_lds_dwordx4 v[224:225], off
	s_mov_b32 m0, s41
	s_nop 0
	global_load_lds_dwordx4 v[226:227], off
	s_waitcnt vmcnt(8)
	s_waitcnt lgkmcnt(0)
	s_barrier
	s_setprio 1
	s_waitcnt lgkmcnt(0)
	v_mfma_f32_16x16x32_bf16 v[124:127], v[138:141], v[174:177], v[124:127]
	v_mfma_f32_16x16x32_bf16 v[116:119], v[150:153], v[174:177], v[116:119]
	v_mfma_f32_16x16x32_bf16 v[108:111], v[138:141], v[182:185], v[108:111]
	v_mfma_f32_16x16x32_bf16 v[96:99], v[150:153], v[182:185], v[96:99]
	v_mfma_f32_16x16x32_bf16 v[88:91], v[138:141], v[190:193], v[88:91]
	v_mfma_f32_16x16x32_bf16 v[80:83], v[150:153], v[190:193], v[80:83]
	v_mfma_f32_16x16x32_bf16 v[72:75], v[138:141], v[212:215], v[72:75]
	v_mfma_f32_16x16x32_bf16 v[64:67], v[150:153], v[212:215], v[64:67]
	v_mfma_f32_16x16x32_bf16 v[124:127], v[142:145], v[178:181], v[124:127]
	v_mfma_f32_16x16x32_bf16 v[116:119], v[154:157], v[178:181], v[116:119]
	v_mfma_f32_16x16x32_bf16 v[108:111], v[142:145], v[186:189], v[108:111]
	v_mfma_f32_16x16x32_bf16 v[96:99], v[154:157], v[186:189], v[96:99]
	v_mfma_f32_16x16x32_bf16 v[88:91], v[142:145], v[194:197], v[88:91]
	v_mfma_f32_16x16x32_bf16 v[80:83], v[154:157], v[194:197], v[80:83]
	v_mfma_f32_16x16x32_bf16 v[72:75], v[142:145], v[216:219], v[72:75]
	v_mfma_f32_16x16x32_bf16 v[64:67], v[154:157], v[216:219], v[64:67]
	s_setprio 0
	s_setprio 1
	v_mfma_f32_16x16x32_bf16 v[120:123], v[158:161], v[174:177], v[120:123]
	v_mfma_f32_16x16x32_bf16 v[112:115], v[166:169], v[174:177], v[112:115]
	v_mfma_f32_16x16x32_bf16 v[104:107], v[158:161], v[182:185], v[104:107]
	v_mfma_f32_16x16x32_bf16 v[100:103], v[166:169], v[182:185], v[100:103]
	v_mfma_f32_16x16x32_bf16 v[92:95], v[158:161], v[190:193], v[92:95]
	v_mfma_f32_16x16x32_bf16 v[84:87], v[166:169], v[190:193], v[84:87]
	v_mfma_f32_16x16x32_bf16 v[76:79], v[158:161], v[212:215], v[76:79]
	v_mfma_f32_16x16x32_bf16 v[68:71], v[166:169], v[212:215], v[68:71]
	v_mfma_f32_16x16x32_bf16 v[120:123], v[162:165], v[178:181], v[120:123]
	v_mfma_f32_16x16x32_bf16 v[112:115], v[170:173], v[178:181], v[112:115]
	v_mfma_f32_16x16x32_bf16 v[104:107], v[162:165], v[186:189], v[104:107]
	v_mfma_f32_16x16x32_bf16 v[100:103], v[170:173], v[186:189], v[100:103]
	v_mfma_f32_16x16x32_bf16 v[92:95], v[162:165], v[194:197], v[92:95]
	v_mfma_f32_16x16x32_bf16 v[84:87], v[170:173], v[194:197], v[84:87]
	v_mfma_f32_16x16x32_bf16 v[76:79], v[162:165], v[216:219], v[76:79]
	v_mfma_f32_16x16x32_bf16 v[68:71], v[170:173], v[216:219], v[68:71]
	s_setprio 0
	s_barrier
	s_add_i32 s0, s59, s38
	v_lshl_add_u64 v[220:221], v[220:221], 0, s[54:55]
	s_mov_b32 m0, s0
	ds_read_b128 v[174:177], v149 offset:49152
	ds_read_b128 v[178:181], v149 offset:50176
	ds_read_b128 v[182:185], v149 offset:51200
	ds_read_b128 v[186:189], v149 offset:52224
	ds_read_b128 v[190:193], v149 offset:53248
	ds_read_b128 v[194:197], v149 offset:54272
	ds_read_b128 v[212:215], v149 offset:55296
	ds_read_b128 v[216:219], v149 offset:56320
	global_load_lds_dwordx4 v[220:221], off
	s_add_i32 m0, s0, 0x2000
	s_add_u32 s0, s28, 0x80080
	v_lshl_add_u64 v[220:221], v[222:223], 0, s[54:55]
	s_addc_u32 s1, s29, 0
	s_add_i32 s28, s63, s38
	global_load_lds_dwordx4 v[220:221], off
	v_lshl_add_u64 v[220:221], s[0:1], 0, v[198:199]
	s_mov_b32 m0, s28
	s_nop 0
	global_load_lds_dwordx4 v[220:221], off
	v_lshl_add_u64 v[220:221], s[0:1], 0, v[128:129]
	s_add_i32 m0, s28, 0x2000
	s_nop 0
	global_load_lds_dwordx4 v[220:221], off
	v_lshl_add_u64 v[220:221], v[224:225], 0, s[54:55]
	s_mov_b32 m0, s47
	s_nop 0
	global_load_lds_dwordx4 v[220:221], off
	v_lshl_add_u64 v[220:221], v[226:227], 0, s[54:55]
	s_mov_b32 m0, s48
	s_nop 0
	global_load_lds_dwordx4 v[220:221], off
	s_waitcnt vmcnt(6)
	s_waitcnt lgkmcnt(0)
	s_barrier
	s_setprio 1
	s_waitcnt lgkmcnt(0)
	v_mfma_f32_16x16x32_bf16 v[56:59], v[138:141], v[174:177], v[56:59]
	v_mfma_f32_16x16x32_bf16 v[48:51], v[150:153], v[174:177], v[48:51]
	v_mfma_f32_16x16x32_bf16 v[40:43], v[138:141], v[182:185], v[40:43]
	v_mfma_f32_16x16x32_bf16 v[32:35], v[150:153], v[182:185], v[32:35]
	v_mfma_f32_16x16x32_bf16 v[24:27], v[138:141], v[190:193], v[24:27]
	v_mfma_f32_16x16x32_bf16 v[16:19], v[150:153], v[190:193], v[16:19]
	v_mfma_f32_16x16x32_bf16 v[8:11], v[138:141], v[212:215], v[8:11]
	v_mfma_f32_16x16x32_bf16 v[0:3], v[150:153], v[212:215], v[0:3]
	v_mfma_f32_16x16x32_bf16 v[56:59], v[142:145], v[178:181], v[56:59]
	v_mfma_f32_16x16x32_bf16 v[48:51], v[154:157], v[178:181], v[48:51]
	v_mfma_f32_16x16x32_bf16 v[40:43], v[142:145], v[186:189], v[40:43]
	v_mfma_f32_16x16x32_bf16 v[32:35], v[154:157], v[186:189], v[32:35]
	v_mfma_f32_16x16x32_bf16 v[24:27], v[142:145], v[194:197], v[24:27]
	v_mfma_f32_16x16x32_bf16 v[16:19], v[154:157], v[194:197], v[16:19]
	v_mfma_f32_16x16x32_bf16 v[8:11], v[142:145], v[216:219], v[8:11]
	v_mfma_f32_16x16x32_bf16 v[0:3], v[154:157], v[216:219], v[0:3]
	s_setprio 0
	s_setprio 1
	v_mfma_f32_16x16x32_bf16 v[60:63], v[158:161], v[174:177], v[60:63]
	v_mfma_f32_16x16x32_bf16 v[52:55], v[166:169], v[174:177], v[52:55]
	v_mfma_f32_16x16x32_bf16 v[44:47], v[158:161], v[182:185], v[44:47]
	v_mfma_f32_16x16x32_bf16 v[36:39], v[166:169], v[182:185], v[36:39]
	v_mfma_f32_16x16x32_bf16 v[28:31], v[158:161], v[190:193], v[28:31]
	v_mfma_f32_16x16x32_bf16 v[20:23], v[166:169], v[190:193], v[20:23]
	v_mfma_f32_16x16x32_bf16 v[12:15], v[158:161], v[212:215], v[12:15]
	v_mfma_f32_16x16x32_bf16 v[4:7], v[166:169], v[212:215], v[4:7]
	v_mfma_f32_16x16x32_bf16 v[60:63], v[162:165], v[178:181], v[60:63]
	v_mfma_f32_16x16x32_bf16 v[52:55], v[170:173], v[178:181], v[52:55]
	v_mfma_f32_16x16x32_bf16 v[44:47], v[162:165], v[186:189], v[44:47]
	v_mfma_f32_16x16x32_bf16 v[36:39], v[170:173], v[186:189], v[36:39]
	v_mfma_f32_16x16x32_bf16 v[28:31], v[162:165], v[194:197], v[28:31]
	v_mfma_f32_16x16x32_bf16 v[20:23], v[170:173], v[194:197], v[20:23]
	v_mfma_f32_16x16x32_bf16 v[12:15], v[162:165], v[216:219], v[12:15]
	v_mfma_f32_16x16x32_bf16 v[4:7], v[170:173], v[216:219], v[4:7]
	s_setprio 0
	s_barrier
	s_add_i32 s61, s61, 2
	s_add_u32 s24, s24, 0x100
	s_addc_u32 s25, s25, 0
	s_add_u32 s35, s35, 0x100
	s_addc_u32 s52, s52, 0
	s_cmp_gt_u32 s61, 29
	s_cbranch_scc0 .LBB0_103
	s_and_b64 vcc, exec, s[12:13]
	s_cbranch_vccz .LBB0_106
	s_barrier

.LBB0_528:
	s_add_u32 s0, s30, 0xfff80080
	s_addc_u32 s1, s31, -1
	s_add_i32 s59, 0, 0x10000
	s_cmp_eq_u32 s61, 28
	s_cselect_b32 s39, s17, s1
	s_cselect_b32 s38, s51, s0
	s_cselect_b32 s37, s15, s52
	s_cselect_b32 s36, s34, s35
	s_add_i32 s63, 0, 0x14000
	v_add_u32_e32 v154, s59, v147
	v_add_u32_e32 v170, s63, v147
	ds_read_b128 v[138:141], v154
	ds_read_b128 v[142:145], v154 offset:1024
	ds_read_b128 v[150:153], v154 offset:2048
	ds_read_b128 v[154:157], v154 offset:3072
	ds_read_b128 v[158:161], v170
	ds_read_b128 v[162:165], v170 offset:1024
	ds_read_b128 v[166:169], v170 offset:2048
	ds_read_b128 v[170:173], v170 offset:3072
	v_lshl_add_u64 v[220:221], s[30:31], 0, v[134:135]
	s_add_i32 m0, s42, 0xc000
	ds_read_b128 v[174:177], v149
	ds_read_b128 v[178:181], v149 offset:1024
	ds_read_b128 v[182:185], v149 offset:2048
	ds_read_b128 v[186:189], v149 offset:3072
	ds_read_b128 v[190:193], v149 offset:4096
	ds_read_b128 v[194:197], v149 offset:5120
	ds_read_b128 v[212:215], v149 offset:6144
	ds_read_b128 v[216:219], v149 offset:7168
	global_load_lds_dwordx4 v[220:221], off
	v_lshl_add_u64 v[220:221], s[30:31], 0, v[136:137]
	s_add_i32 m0, s42, 0xe000
	s_nop 0
	global_load_lds_dwordx4 v[220:221], off
	s_waitcnt vmcnt(8)
	s_waitcnt lgkmcnt(0)
	s_barrier
	s_setprio 1
	s_waitcnt lgkmcnt(0)
	v_mfma_f32_16x16x32_bf16 v[124:127], v[138:141], v[174:177], v[124:127]
	v_mfma_f32_16x16x32_bf16 v[116:119], v[150:153], v[174:177], v[116:119]
	v_mfma_f32_16x16x32_bf16 v[108:111], v[138:141], v[182:185], v[108:111]
	v_mfma_f32_16x16x32_bf16 v[96:99], v[150:153], v[182:185], v[96:99]
	v_mfma_f32_16x16x32_bf16 v[88:91], v[138:141], v[190:193], v[88:91]
	v_mfma_f32_16x16x32_bf16 v[80:83], v[150:153], v[190:193], v[80:83]
	v_mfma_f32_16x16x32_bf16 v[72:75], v[138:141], v[212:215], v[72:75]
	v_mfma_f32_16x16x32_bf16 v[64:67], v[150:153], v[212:215], v[64:67]
	v_mfma_f32_16x16x32_bf16 v[124:127], v[142:145], v[178:181], v[124:127]
	v_mfma_f32_16x16x32_bf16 v[116:119], v[154:157], v[178:181], v[116:119]
	v_mfma_f32_16x16x32_bf16 v[108:111], v[142:145], v[186:189], v[108:111]
	v_mfma_f32_16x16x32_bf16 v[96:99], v[154:157], v[186:189], v[96:99]
	v_mfma_f32_16x16x32_bf16 v[88:91], v[142:145], v[194:197], v[88:91]
	v_mfma_f32_16x16x32_bf16 v[80:83], v[154:157], v[194:197], v[80:83]
	v_mfma_f32_16x16x32_bf16 v[72:75], v[142:145], v[216:219], v[72:75]
	v_mfma_f32_16x16x32_bf16 v[64:67], v[154:157], v[216:219], v[64:67]
	s_setprio 0
	s_setprio 1
	v_mfma_f32_16x16x32_bf16 v[120:123], v[158:161], v[174:177], v[120:123]
	v_mfma_f32_16x16x32_bf16 v[112:115], v[166:169], v[174:177], v[112:115]
	v_mfma_f32_16x16x32_bf16 v[104:107], v[158:161], v[182:185], v[104:107]
	v_mfma_f32_16x16x32_bf16 v[100:103], v[166:169], v[182:185], v[100:103]
	v_mfma_f32_16x16x32_bf16 v[92:95], v[158:161], v[190:193], v[92:95]
	v_mfma_f32_16x16x32_bf16 v[84:87], v[166:169], v[190:193], v[84:87]
	v_mfma_f32_16x16x32_bf16 v[76:79], v[158:161], v[212:215], v[76:79]
	v_mfma_f32_16x16x32_bf16 v[68:71], v[166:169], v[212:215], v[68:71]
	v_mfma_f32_16x16x32_bf16 v[120:123], v[162:165], v[178:181], v[120:123]
	v_mfma_f32_16x16x32_bf16 v[112:115], v[170:173], v[178:181], v[112:115]
	v_mfma_f32_16x16x32_bf16 v[104:107], v[162:165], v[186:189], v[104:107]
	v_mfma_f32_16x16x32_bf16 v[100:103], v[170:173], v[186:189], v[100:103]
	v_mfma_f32_16x16x32_bf16 v[92:95], v[162:165], v[194:197], v[92:95]
	v_mfma_f32_16x16x32_bf16 v[84:87], v[170:173], v[194:197], v[84:87]
	v_mfma_f32_16x16x32_bf16 v[76:79], v[162:165], v[216:219], v[76:79]
	v_mfma_f32_16x16x32_bf16 v[68:71], v[170:173], v[216:219], v[68:71]
	s_setprio 0
	s_barrier
	s_add_i32 s0, s59, s40
	v_lshl_add_u64 v[220:221], s[36:37], 0, v[198:199]
	s_mov_b32 m0, s0
	ds_read_b128 v[174:177], v149 offset:16384
	ds_read_b128 v[178:181], v149 offset:17408
	ds_read_b128 v[182:185], v149 offset:18432
	ds_read_b128 v[186:189], v149 offset:19456
	ds_read_b128 v[190:193], v149 offset:20480
	ds_read_b128 v[194:197], v149 offset:21504
	ds_read_b128 v[212:215], v149 offset:22528
	ds_read_b128 v[216:219], v149 offset:23552
	global_load_lds_dwordx4 v[220:221], off
	s_add_i32 m0, s0, 0x2000
	s_add_u32 s0, s36, 0x80000
	v_lshl_add_u64 v[222:223], s[36:37], 0, v[128:129]
	s_addc_u32 s1, s37, 0
	s_add_i32 s59, s63, s40
	global_load_lds_dwordx4 v[222:223], off
	v_lshl_add_u64 v[224:225], s[0:1], 0, v[198:199]
	s_mov_b32 m0, s59
	v_lshl_add_u64 v[226:227], s[38:39], 0, v[130:131]
	global_load_lds_dwordx4 v[224:225], off
	v_lshl_add_u64 v[224:225], s[0:1], 0, v[128:129]
	s_add_i32 m0, s59, 0x2000
	s_nop 0
	global_load_lds_dwordx4 v[224:225], off
	s_waitcnt vmcnt(6)
	s_waitcnt lgkmcnt(0)
	s_barrier
	s_setprio 1
	s_waitcnt lgkmcnt(0)
	v_mfma_f32_16x16x32_bf16 v[56:59], v[138:141], v[174:177], v[56:59]
	v_mfma_f32_16x16x32_bf16 v[48:51], v[150:153], v[174:177], v[48:51]
	v_mfma_f32_16x16x32_bf16 v[40:43], v[138:141], v[182:185], v[40:43]
	v_mfma_f32_16x16x32_bf16 v[32:35], v[150:153], v[182:185], v[32:35]
	v_mfma_f32_16x16x32_bf16 v[24:27], v[138:141], v[190:193], v[24:27]
	v_mfma_f32_16x16x32_bf16 v[16:19], v[150:153], v[190:193], v[16:19]
	v_mfma_f32_16x16x32_bf16 v[8:11], v[138:141], v[212:215], v[8:11]
	v_mfma_f32_16x16x32_bf16 v[0:3], v[150:153], v[212:215], v[0:3]
	v_mfma_f32_16x16x32_bf16 v[56:59], v[142:145], v[178:181], v[56:59]
	v_mfma_f32_16x16x32_bf16 v[48:51], v[154:157], v[178:181], v[48:51]
	v_mfma_f32_16x16x32_bf16 v[40:43], v[142:145], v[186:189], v[40:43]
	v_mfma_f32_16x16x32_bf16 v[32:35], v[154:157], v[186:189], v[32:35]
	v_mfma_f32_16x16x32_bf16 v[24:27], v[142:145], v[194:197], v[24:27]
	v_mfma_f32_16x16x32_bf16 v[16:19], v[154:157], v[194:197], v[16:19]
	v_mfma_f32_16x16x32_bf16 v[8:11], v[142:145], v[216:219], v[8:11]
	v_mfma_f32_16x16x32_bf16 v[0:3], v[154:157], v[216:219], v[0:3]
	s_setprio 0
	s_setprio 1
	v_mfma_f32_16x16x32_bf16 v[60:63], v[158:161], v[174:177], v[60:63]
	v_mfma_f32_16x16x32_bf16 v[52:55], v[166:169], v[174:177], v[52:55]
	v_mfma_f32_16x16x32_bf16 v[44:47], v[158:161], v[182:185], v[44:47]
	v_mfma_f32_16x16x32_bf16 v[36:39], v[166:169], v[182:185], v[36:39]
	v_mfma_f32_16x16x32_bf16 v[28:31], v[158:161], v[190:193], v[28:31]
	v_mfma_f32_16x16x32_bf16 v[20:23], v[166:169], v[190:193], v[20:23]
	v_mfma_f32_16x16x32_bf16 v[12:15], v[158:161], v[212:215], v[12:15]
	v_mfma_f32_16x16x32_bf16 v[4:7], v[166:169], v[212:215], v[4:7]
	v_mfma_f32_16x16x32_bf16 v[60:63], v[162:165], v[178:181], v[60:63]
	v_mfma_f32_16x16x32_bf16 v[52:55], v[170:173], v[178:181], v[52:55]
	v_mfma_f32_16x16x32_bf16 v[44:47], v[162:165], v[186:189], v[44:47]
	v_mfma_f32_16x16x32_bf16 v[36:39], v[170:173], v[186:189], v[36:39]
	v_mfma_f32_16x16x32_bf16 v[28:31], v[162:165], v[194:197], v[28:31]
	v_mfma_f32_16x16x32_bf16 v[20:23], v[170:173], v[194:197], v[20:23]
	v_mfma_f32_16x16x32_bf16 v[12:15], v[162:165], v[216:219], v[12:15]
	v_mfma_f32_16x16x32_bf16 v[4:7], v[170:173], v[216:219], v[4:7]
	s_setprio 0
	s_barrier
	s_add_i32 s59, 0, 0x18000
	s_add_i32 s63, 0, 0x1c000
	v_add_u32_e32 v154, s59, v147
	v_add_u32_e32 v170, s63, v147
	ds_read_b128 v[138:141], v154
	ds_read_b128 v[142:145], v154 offset:1024
	ds_read_b128 v[150:153], v154 offset:2048
	ds_read_b128 v[154:157], v154 offset:3072
	ds_read_b128 v[158:161], v170
	ds_read_b128 v[162:165], v170 offset:1024
	ds_read_b128 v[166:169], v170 offset:2048
	ds_read_b128 v[170:173], v170 offset:3072
	s_add_u32 s0, s38, 0x80000
	s_addc_u32 s1, s39, 0
	s_mov_b32 m0, s44
	v_lshl_add_u64 v[228:229], s[0:1], 0, v[132:133]
	ds_read_b128 v[174:177], v149 offset:32768
	ds_read_b128 v[178:181], v149 offset:33792
	ds_read_b128 v[182:185], v149 offset:34816
	ds_read_b128 v[186:189], v149 offset:35840
	ds_read_b128 v[190:193], v149 offset:36864
	ds_read_b128 v[194:197], v149 offset:37888
	ds_read_b128 v[212:215], v149 offset:38912
	ds_read_b128 v[216:219], v149 offset:39936
	global_load_lds_dwordx4 v[228:229], off
	v_lshl_add_u64 v[228:229], s[0:1], 0, v[130:131]
	s_mov_b32 m0, s45
	s_nop 0
	global_load_lds_dwordx4 v[228:229], off
	v_lshl_add_u64 v[224:225], s[38:39], 0, v[132:133]
	s_mov_b32 m0, s42
	s_nop 0
	global_load_lds_dwordx4 v[224:225], off
	s_mov_b32 m0, s43
	s_nop 0
	global_load_lds_dwordx4 v[226:227], off
	s_waitcnt vmcnt(8)
	s_waitcnt lgkmcnt(0)
	s_barrier
	s_setprio 1
	s_waitcnt lgkmcnt(0)
	v_mfma_f32_16x16x32_bf16 v[124:127], v[138:141], v[174:177], v[124:127]
	v_mfma_f32_16x16x32_bf16 v[116:119], v[150:153], v[174:177], v[116:119]
	v_mfma_f32_16x16x32_bf16 v[108:111], v[138:141], v[182:185], v[108:111]
	v_mfma_f32_16x16x32_bf16 v[96:99], v[150:153], v[182:185], v[96:99]
	v_mfma_f32_16x16x32_bf16 v[88:91], v[138:141], v[190:193], v[88:91]
	v_mfma_f32_16x16x32_bf16 v[80:83], v[150:153], v[190:193], v[80:83]
	v_mfma_f32_16x16x32_bf16 v[72:75], v[138:141], v[212:215], v[72:75]
	v_mfma_f32_16x16x32_bf16 v[64:67], v[150:153], v[212:215], v[64:67]
	v_mfma_f32_16x16x32_bf16 v[124:127], v[142:145], v[178:181], v[124:127]
	v_mfma_f32_16x16x32_bf16 v[116:119], v[154:157], v[178:181], v[116:119]
	v_mfma_f32_16x16x32_bf16 v[108:111], v[142:145], v[186:189], v[108:111]
	v_mfma_f32_16x16x32_bf16 v[96:99], v[154:157], v[186:189], v[96:99]
	v_mfma_f32_16x16x32_bf16 v[88:91], v[142:145], v[194:197], v[88:91]
	v_mfma_f32_16x16x32_bf16 v[80:83], v[154:157], v[194:197], v[80:83]
	v_mfma_f32_16x16x32_bf16 v[72:75], v[142:145], v[216:219], v[72:75]
	v_mfma_f32_16x16x32_bf16 v[64:67], v[154:157], v[216:219], v[64:67]
	s_setprio 0
	s_setprio 1
	v_mfma_f32_16x16x32_bf16 v[120:123], v[158:161], v[174:177], v[120:123]
	v_mfma_f32_16x16x32_bf16 v[112:115], v[166:169], v[174:177], v[112:115]
	v_mfma_f32_16x16x32_bf16 v[104:107], v[158:161], v[182:185], v[104:107]
	v_mfma_f32_16x16x32_bf16 v[100:103], v[166:169], v[182:185], v[100:103]
	v_mfma_f32_16x16x32_bf16 v[92:95], v[158:161], v[190:193], v[92:95]
	v_mfma_f32_16x16x32_bf16 v[84:87], v[166:169], v[190:193], v[84:87]
	v_mfma_f32_16x16x32_bf16 v[76:79], v[158:161], v[212:215], v[76:79]
	v_mfma_f32_16x16x32_bf16 v[68:71], v[166:169], v[212:215], v[68:71]
	v_mfma_f32_16x16x32_bf16 v[120:123], v[162:165], v[178:181], v[120:123]
	v_mfma_f32_16x16x32_bf16 v[112:115], v[170:173], v[178:181], v[112:115]
	v_mfma_f32_16x16x32_bf16 v[104:107], v[162:165], v[186:189], v[104:107]
	v_mfma_f32_16x16x32_bf16 v[100:103], v[170:173], v[186:189], v[100:103]
	v_mfma_f32_16x16x32_bf16 v[92:95], v[162:165], v[194:197], v[92:95]
	v_mfma_f32_16x16x32_bf16 v[84:87], v[170:173], v[194:197], v[84:87]
	v_mfma_f32_16x16x32_bf16 v[76:79], v[162:165], v[216:219], v[76:79]
	v_mfma_f32_16x16x32_bf16 v[68:71], v[170:173], v[216:219], v[68:71]
	s_setprio 0
	s_barrier
	s_add_i32 s0, s59, s40
	v_lshl_add_u64 v[220:221], v[220:221], 0, s[54:55]
	s_mov_b32 m0, s0
	ds_read_b128 v[174:177], v149 offset:49152
	ds_read_b128 v[178:181], v149 offset:50176
	ds_read_b128 v[182:185], v149 offset:51200
	ds_read_b128 v[186:189], v149 offset:52224
	ds_read_b128 v[190:193], v149 offset:53248
	ds_read_b128 v[194:197], v149 offset:54272
	ds_read_b128 v[212:215], v149 offset:55296
	ds_read_b128 v[216:219], v149 offset:56320
	global_load_lds_dwordx4 v[220:221], off
	s_add_i32 m0, s0, 0x2000
	s_add_u32 s0, s36, 0x80080
	v_lshl_add_u64 v[220:221], v[222:223], 0, s[54:55]
	s_addc_u32 s1, s37, 0
	s_add_i32 s36, s63, s40
	global_load_lds_dwordx4 v[220:221], off
	v_lshl_add_u64 v[220:221], s[0:1], 0, v[198:199]
	s_mov_b32 m0, s36
	s_nop 0
	global_load_lds_dwordx4 v[220:221], off
	v_lshl_add_u64 v[220:221], s[0:1], 0, v[128:129]
	s_add_i32 m0, s36, 0x2000
	s_nop 0
	global_load_lds_dwordx4 v[220:221], off
	v_lshl_add_u64 v[220:221], v[224:225], 0, s[54:55]
	s_mov_b32 m0, s47
	s_nop 0
	global_load_lds_dwordx4 v[220:221], off
	v_lshl_add_u64 v[220:221], v[226:227], 0, s[54:55]
	s_mov_b32 m0, s48
	s_nop 0
	global_load_lds_dwordx4 v[220:221], off
	s_waitcnt vmcnt(6)
	s_waitcnt lgkmcnt(0)
	s_barrier
	s_setprio 1
	s_waitcnt lgkmcnt(0)
	v_mfma_f32_16x16x32_bf16 v[56:59], v[138:141], v[174:177], v[56:59]
	v_mfma_f32_16x16x32_bf16 v[48:51], v[150:153], v[174:177], v[48:51]
	v_mfma_f32_16x16x32_bf16 v[40:43], v[138:141], v[182:185], v[40:43]
	v_mfma_f32_16x16x32_bf16 v[32:35], v[150:153], v[182:185], v[32:35]
	v_mfma_f32_16x16x32_bf16 v[24:27], v[138:141], v[190:193], v[24:27]
	v_mfma_f32_16x16x32_bf16 v[16:19], v[150:153], v[190:193], v[16:19]
	v_mfma_f32_16x16x32_bf16 v[8:11], v[138:141], v[212:215], v[8:11]
	v_mfma_f32_16x16x32_bf16 v[0:3], v[150:153], v[212:215], v[0:3]
	v_mfma_f32_16x16x32_bf16 v[56:59], v[142:145], v[178:181], v[56:59]
	v_mfma_f32_16x16x32_bf16 v[48:51], v[154:157], v[178:181], v[48:51]
	v_mfma_f32_16x16x32_bf16 v[40:43], v[142:145], v[186:189], v[40:43]
	v_mfma_f32_16x16x32_bf16 v[32:35], v[154:157], v[186:189], v[32:35]
	v_mfma_f32_16x16x32_bf16 v[24:27], v[142:145], v[194:197], v[24:27]
	v_mfma_f32_16x16x32_bf16 v[16:19], v[154:157], v[194:197], v[16:19]
	v_mfma_f32_16x16x32_bf16 v[8:11], v[142:145], v[216:219], v[8:11]
	v_mfma_f32_16x16x32_bf16 v[0:3], v[154:157], v[216:219], v[0:3]
	s_setprio 0
	s_setprio 1
	v_mfma_f32_16x16x32_bf16 v[60:63], v[158:161], v[174:177], v[60:63]
	v_mfma_f32_16x16x32_bf16 v[52:55], v[166:169], v[174:177], v[52:55]
	v_mfma_f32_16x16x32_bf16 v[44:47], v[158:161], v[182:185], v[44:47]
	v_mfma_f32_16x16x32_bf16 v[36:39], v[166:169], v[182:185], v[36:39]
	v_mfma_f32_16x16x32_bf16 v[28:31], v[158:161], v[190:193], v[28:31]
	v_mfma_f32_16x16x32_bf16 v[20:23], v[166:169], v[190:193], v[20:23]
	v_mfma_f32_16x16x32_bf16 v[12:15], v[158:161], v[212:215], v[12:15]
	v_mfma_f32_16x16x32_bf16 v[4:7], v[166:169], v[212:215], v[4:7]
	v_mfma_f32_16x16x32_bf16 v[60:63], v[162:165], v[178:181], v[60:63]
	v_mfma_f32_16x16x32_bf16 v[52:55], v[170:173], v[178:181], v[52:55]
	v_mfma_f32_16x16x32_bf16 v[44:47], v[162:165], v[186:189], v[44:47]
	v_mfma_f32_16x16x32_bf16 v[36:39], v[170:173], v[186:189], v[36:39]
	v_mfma_f32_16x16x32_bf16 v[28:31], v[162:165], v[194:197], v[28:31]
	v_mfma_f32_16x16x32_bf16 v[20:23], v[170:173], v[194:197], v[20:23]
	v_mfma_f32_16x16x32_bf16 v[12:15], v[162:165], v[216:219], v[12:15]
	v_mfma_f32_16x16x32_bf16 v[4:7], v[170:173], v[216:219], v[4:7]
	s_setprio 0
	s_barrier
	s_add_i32 s61, s61, 2
	s_add_u32 s30, s30, 0x100
	s_addc_u32 s31, s31, 0
	s_add_u32 s35, s35, 0x100
	s_addc_u32 s52, s52, 0
	s_cmp_gt_u32 s61, 29
	s_cbranch_scc0 .LBB0_528
	s_and_b64 vcc, exec, s[12:13]
	s_cbranch_vccz .LBB0_531
	s_barrier
